# late-scan prefetch extended: G and SA0 (merge-phase inputs), then XB and WIN rows 3584.. over scan intervals 42-62
# baseline (speedup 1.0000x reference)
.Lcv_noitem:
	s_sub_u32 s54, s12, 42
	s_cmp_lt_u32 s54, 21
	s_cbranch_scc0 .Lpf_skip
	s_lshl_b32 s54, s54, 10
	s_lshl_b32 s53, s8, 2
	s_add_i32 s53, s53, s11
	s_add_i32 s53, s53, -4
	s_add_i32 s54, s54, s53
	s_cmp_lt_u32 s54, 0x52a0
	s_cbranch_scc0 .Lpf_skip
	s_cmp_lt_u32 s54, 0x2080
	s_cbranch_scc0 .Lpf_s1
	s_lshl_b32 s55, s54, 12
	s_add_u32 s56, s86, 0x12c48000
	s_addc_u32 s57, s87, 0
	s_add_u32 s56, s56, s55
	s_addc_u32 s57, s57, 0
	s_branch .Lpf_go
.Lpf_s1:
	s_cmp_lt_u32 s54, 0x28a0
	s_cbranch_scc0 .Lpf_s2
	s_sub_u32 s54, s54, 0x2080
	s_lshl_b32 s55, s54, 12
	s_add_u32 s56, s86, 0x14ccc000
	s_addc_u32 s57, s87, 0
	s_add_u32 s56, s56, s55
	s_addc_u32 s57, s57, 0
	s_branch .Lpf_go
.Lpf_s2:
	s_cmp_lt_u32 s54, 0x4920
	s_cbranch_scc0 .Lpf_s3
	s_sub_u32 s54, s54, 0x28a0
	s_lshl_b32 s55, s54, 12
	s_add_u32 s56, s84, s55
	s_addc_u32 s57, s85, 0
	s_branch .Lpf_go
.Lpf_s3:
	s_sub_u32 s54, s54, 0x4920
	s_lshl_b32 s55, s54, 12
	s_add_u32 s56, s86, 0x1780000
	s_addc_u32 s57, s87, 0
	s_add_u32 s56, s56, s55
	s_addc_u32 s57, s57, 0

.LBB0_606:
	s_and_b64 vcc, exec, s[0:1]
	s_cbranch_vccz .LBB0_508
	s_waitcnt vmcnt(0)
	v_lshrrev_b32_e32 v90, 4, v241
	v_bfe_u32 v91, v241, 3, 1
	v_and_b32_e32 v86, 15, v241
	v_lshlrev_b32_e32 v90, 1, v90
	v_lshlrev_b32_e32 v86, 4, v86
	v_add_u32_e32 v92, v90, v91
	v_xor_b32_e32 v91, 1, v91
	v_add_u32_e32 v93, v90, v91
	s_lshl_b32 s0, s10, 5
	v_lshlrev_b32_e32 v89, 2, v92
	v_add_u32_e32 v92, s0, v92
	v_add_u32_e32 v93, s0, v93
	v_add_u32_e32 v89, 0x18000, v89
	v_lshlrev_b32_e32 v87, 2, v92
	v_lshlrev_b32_e32 v88, 2, v93
	v_mov_b32_e32 v0, 0
	v_mov_b32_e32 v1, 0
	v_mov_b32_e32 v2, 0
	v_mov_b32_e32 v3, 0
	v_mov_b32_e32 v4, 0
	v_mov_b32_e32 v5, 0
	v_mov_b32_e32 v6, 0
	v_mov_b32_e32 v7, 0
	s_waitcnt lgkmcnt(0)
	s_barrier
	s_mov_b32 s4, 0
	s_nop 0
	s_nop 0
	s_nop 0
	s_nop 0
	s_nop 0
	s_nop 0
	s_nop 0
	s_nop 0
	s_nop 0
	s_nop 0
	s_nop 0
	s_nop 0
